# P5 mid-K hook: seam-1 counter + 16 ssq loads per thread requested inside the first K-loop (last 3 iterations), hook only sums when counter was already 4; on top of v23
# baseline (speedup 1.0000x reference)
; #define PG8_STAGE(bufoff, gbase, voff) do { _Pragma("unroll") for (int _i = 0; _i < 2; ++_i) \
;         __builtin_amdgcn_global_load_lds((const unsigned*)((const char*)(gbase) + (voff)[_i]), (PG8_LAS unsigned*)(lds + (bufoff) + ldsw + _i * 8192), 16, 0, 0); } while (0)
; #define PG8_WAIT_V(n) asm volatile("s_waitcnt vmcnt(" #n ")" ::: "memory")
; #define PG8_BAR __builtin_amdgcn_s_barrier()
; template <int ROT, class Epi0, class Epi1, class Late, class Post0>
; __device__ __forceinline__ void gemm_phase_pair(PG8_LAS unsigned char* lds, const Gemm g0, const Gemm g1, const Unit u, const Epi0& E0, const Epi1& E1, int wid_in, const Late& late, const Post0& post0) {
;     ...
;     for (int i = 0; i < 2; ++i) { int R, C; stage_rc(tid * 16 + i * 8192, R, C); const int Rb0 = Epi0::PERM ? ((R & ~31) + perm32(R & 31)) : R;
;         vA0[i] = (unsigned)(R * K0 + C) * 2u; vB0[i] = (unsigned)(Rb0 * K0 + C) * 2u; }
;     ...
;     const size_t kstep = (size_t)(BK * 2);
;     const size_t hs0 = (size_t)HALF * K0 * 2, hs1 = (size_t)HALF * K1 * 2;
;     const unsigned ldsw = (unsigned)wid * 1024u;
;     const int aoff = lds_byte(wr * 64 + fr, fq * 8), boff = lds_byte(wc * 32 + fr, fq * 8);
;     f32x4 acc[2][2][4][2];
; #pragma unroll
;     for (int a = 0; a < 2; ++a)
; #pragma unroll
;         for (int b = 0; b < 2; ++b)
; #pragma unroll
;             for (int m = 0; m < 4; ++m)
; #pragma unroll
;                 for (int n = 0; n < 2; ++n) acc[a][b][m][n] = (f32x4){0.f, 0.f, 0.f, 0.f};
;     bf16x8 At[4][2], B0[2][2], B1[2][2];
;     const char* cA = (const char*)g0.A + (size_t)u.pm * 2 * hs0; const char* cB = (const char*)g0.Bt + (size_t)u.pn * 2 * hs0;
;     const char* nA = (const char*)g1.A + (size_t)u.pm * 2 * hs1; const char* nB = (const char*)g1.Bt + (size_t)u.pn * 2 * hs1;
;     ...
;     PG8_STAGE(PG8_SB(0, 0), cB + PG8_KT(0), vB0); PG8_STAGE(PG8_SB(0, 1), cB + hs0 + PG8_KT(0), vB0); PG8_STAGE(PG8_SA(0, 0), cA + PG8_KT(0), vA0); PG8_STAGE(PG8_SA(0, 1), cA + hs0 + PG8_KT(0), vA0);
;     if (wr == 1) PG8_BAR;
;     PG8_WAIT_V(2); PG8_BAR;
;     PG8_STAGE(PG8_SB(1, 0), cB + PG8_KT(1), vB0); PG8_STAGE(PG8_SA(1, 0), cA + PG8_KT(1), vA0); PG8_STAGE(PG8_SB(1, 1), cB + hs0 + PG8_KT(1), vB0);
;     PG8_WAIT_V(6); PG8_BAR;
.LBB0_846:
	v_readlane_b32 s7, v252, 5
	s_lshl_b32 s7, s7, 5
	s_and_b32 s52, s7, 0x60
	s_lshl_b32 s12, s6, 6
	v_ashrrev_i32_e32 v1, 6, v143
	s_lshr_b32 s7, s52, 3
	s_lshl_b32 s6, s6, 13
	v_lshl_add_u32 v12, v1, 10, s6
	v_add_lshl_u32 v1, v1, s7, 10
	s_mov_b64 s[6:7], 0x880
	s_add_i32 m0, s40, 0x18000
	v_lshl_add_u64 v[2:3], v[2:3], 0, s[6:7]
	s_waitcnt vmcnt(2)
	s_barrier
	global_load_lds_dwordx4 v[2:3], off
	v_lshl_add_u64 v[2:3], v[4:5], 0, s[6:7]
	s_add_i32 m0, s40, 0x1a000
	s_add_i32 s13, s40, 0x8000
	s_add_i32 s33, s40, 0xa000
	global_load_lds_dwordx4 v[2:3], off
	v_lshl_add_u64 v[2:3], v[6:7], 0, s[6:7]
	s_mov_b32 m0, s13
	s_add_u32 s4, s4, 0x80880
	global_load_lds_dwordx4 v[2:3], off
	v_lshl_add_u64 v[2:3], v[8:9], 0, s[6:7]
	s_mov_b32 m0, s33
	s_addc_u32 s5, s5, 0
	global_load_lds_dwordx4 v[2:3], off
	s_add_i32 m0, s40, 0x1c000
	v_lshl_add_u64 v[2:3], s[4:5], 0, v[132:133]
	global_load_lds_dwordx4 v[2:3], off
	v_lshl_add_u64 v[2:3], s[4:5], 0, v[130:131]
	s_add_i32 m0, s40, 0x1e000
	v_and_b32_e32 v136, 15, v143
	global_load_lds_dwordx4 v[2:3], off
	v_and_b32_e32 v10, 48, v143
	v_lshlrev_b32_e32 v11, 2, v143
	v_lshl_or_b32 v10, v136, 6, v10
	v_and_b32_e32 v11, 32, v11
	v_bitop3_b32 v1, v10, v1, v11 bitop3:0xde
	s_waitcnt vmcnt(6)
	s_add_i32 s49, 0, 0x10000
	s_add_i32 s48, 0, 0x14000
	s_add_i32 s44, 0, 0x18000
	s_add_i32 s43, 0, 0x1c000
	v_bitop3_b32 v10, v10, v12, v11 bitop3:0xde
	v_add_u32_e32 v141, s49, v1
	v_add_u32_e32 v140, s48, v1
	s_add_i32 s49, s49, s36
	s_add_i32 s48, s48, s36
	v_add_u32_e32 v139, s44, v1
	v_add_u32_e32 v138, s43, v1
	s_add_i32 s44, s44, s36
	s_add_i32 s43, s43, s36
	v_or_b32_e32 v142, s12, v136
	v_add_u32_e32 v137, 0, v10
	s_mov_b32 s53, -2
	s_mov_b64 s[4:5], 0x8c80880
	s_add_i32 s51, s40, 0xc000
	s_add_i32 s50, s40, 0xe000
	s_mov_b64 s[6:7], 0xd00900
	s_add_i32 s47, s49, 0x2000
	s_mov_b64 s[10:11], 0xd80900
	s_add_i32 s46, s48, 0x2000
	s_mov_b64 s[24:25], 0x8c00900
	s_mov_b64 s[26:27], 0x8c80900
	s_mov_b64 s[28:29], 0xd00980
	s_add_i32 s42, s44, 0x2000
	s_mov_b64 s[30:31], 0xd80980
	s_add_i32 s41, s43, 0x2000
	s_mov_b64 s[36:37], 0x8c00980
	s_mov_b64 s[38:39], s[96:97]
	v_mov_b32_e32 v134, v130
	v_mov_b32_e32 v130, v0
	v_mov_b32_e32 v0, v131
	v_mov_b32_e32 v1, v131
	v_mov_b32_e32 v2, v131
	v_mov_b32_e32 v3, v131
	v_mov_b32_e32 v4, v131
	v_mov_b32_e32 v5, v131
	v_mov_b32_e32 v6, v131
	v_mov_b32_e32 v7, v131
	v_mov_b32_e32 v8, v131
	v_mov_b32_e32 v9, v131
	v_mov_b32_e32 v10, v131
	v_mov_b32_e32 v11, v131
	v_mov_b32_e32 v12, v131
	v_mov_b32_e32 v13, v131
	v_mov_b32_e32 v14, v131
	v_mov_b32_e32 v15, v131
	v_mov_b32_e32 v16, v131
	v_mov_b32_e32 v17, v131
	v_mov_b32_e32 v18, v131
	v_mov_b32_e32 v19, v131
	v_mov_b32_e32 v20, v131
	v_mov_b32_e32 v21, v131
	v_mov_b32_e32 v22, v131
	v_mov_b32_e32 v23, v131
	v_mov_b32_e32 v24, v131
	v_mov_b32_e32 v25, v131
	v_mov_b32_e32 v26, v131
	v_mov_b32_e32 v27, v131
	v_mov_b32_e32 v28, v131
	v_mov_b32_e32 v29, v131
	v_mov_b32_e32 v30, v131
	v_mov_b32_e32 v31, v131
	v_mov_b32_e32 v32, v131
	v_mov_b32_e32 v33, v131
	v_mov_b32_e32 v34, v131
	v_mov_b32_e32 v35, v131
	v_mov_b32_e32 v36, v131
	v_mov_b32_e32 v37, v131
	v_mov_b32_e32 v38, v131
	v_mov_b32_e32 v39, v131
	v_mov_b32_e32 v40, v131
	v_mov_b32_e32 v41, v131
	v_mov_b32_e32 v42, v131
	v_mov_b32_e32 v43, v131
	v_mov_b32_e32 v44, v131
	v_mov_b32_e32 v45, v131
	v_mov_b32_e32 v46, v131
	v_mov_b32_e32 v47, v131
	v_mov_b32_e32 v48, v131
	v_mov_b32_e32 v49, v131
	v_mov_b32_e32 v50, v131
	v_mov_b32_e32 v51, v131
	v_mov_b32_e32 v52, v131
	v_mov_b32_e32 v53, v131
	v_mov_b32_e32 v54, v131
	v_mov_b32_e32 v55, v131
	v_mov_b32_e32 v56, v131
	v_mov_b32_e32 v57, v131
	v_mov_b32_e32 v58, v131
	v_mov_b32_e32 v59, v131
	v_mov_b32_e32 v60, v131
	v_mov_b32_e32 v61, v131
	v_mov_b32_e32 v62, v131
	v_mov_b32_e32 v63, v131
	v_mov_b32_e32 v64, v131
	v_mov_b32_e32 v65, v131
	v_mov_b32_e32 v66, v131
	v_mov_b32_e32 v67, v131
	v_mov_b32_e32 v68, v131
	v_mov_b32_e32 v69, v131
	v_mov_b32_e32 v70, v131
	v_mov_b32_e32 v71, v131
	v_mov_b32_e32 v72, v131
	v_mov_b32_e32 v73, v131
	v_mov_b32_e32 v74, v131
	v_mov_b32_e32 v75, v131
	v_mov_b32_e32 v76, v131
	v_mov_b32_e32 v77, v131
	v_mov_b32_e32 v78, v131
	v_mov_b32_e32 v79, v131
	v_mov_b32_e32 v80, v131
	v_mov_b32_e32 v81, v131
	v_mov_b32_e32 v82, v131
	v_mov_b32_e32 v83, v131
	v_mov_b32_e32 v84, v131
	v_mov_b32_e32 v85, v131
	v_mov_b32_e32 v86, v131
	v_mov_b32_e32 v87, v131
	v_mov_b32_e32 v88, v131
	v_mov_b32_e32 v89, v131
	v_mov_b32_e32 v90, v131
	v_mov_b32_e32 v91, v131
	v_mov_b32_e32 v92, v131
	v_mov_b32_e32 v93, v131
	v_mov_b32_e32 v94, v131
	v_mov_b32_e32 v95, v131
	v_mov_b32_e32 v96, v131
	v_mov_b32_e32 v97, v131
	v_mov_b32_e32 v98, v131
	v_mov_b32_e32 v99, v131
	v_mov_b32_e32 v100, v131
	v_mov_b32_e32 v101, v131
	v_mov_b32_e32 v102, v131
	v_mov_b32_e32 v103, v131
	v_mov_b32_e32 v104, v131
	v_mov_b32_e32 v105, v131
	v_mov_b32_e32 v106, v131
	v_mov_b32_e32 v107, v131
	v_mov_b32_e32 v108, v131
	v_mov_b32_e32 v109, v131
	v_mov_b32_e32 v110, v131
	v_mov_b32_e32 v111, v131
	v_mov_b32_e32 v112, v131
	v_mov_b32_e32 v113, v131
	v_mov_b32_e32 v114, v131
	v_mov_b32_e32 v115, v131
	v_mov_b32_e32 v116, v131
	v_mov_b32_e32 v117, v131
	v_mov_b32_e32 v118, v131
	v_mov_b32_e32 v119, v131
	v_mov_b32_e32 v120, v131
	v_mov_b32_e32 v121, v131
	v_mov_b32_e32 v122, v131
	v_mov_b32_e32 v123, v131
	v_mov_b32_e32 v124, v131
	v_mov_b32_e32 v125, v131
	v_mov_b32_e32 v126, v131
	v_mov_b32_e32 v127, v131
	s_barrier
	s_mov_b32 s98, 0
; __device__ __forceinline__ int hw_lane() { int l; asm volatile("v_mbcnt_lo_u32_b32 %0, -1, 0\n\tv_mbcnt_hi_u32_b32 %0, -1, %0" : "=v"(l)); return l; }
; __device__ __forceinline__ unsigned xb_ld(unsigned* p)              { return __hip_atomic_load(p, __ATOMIC_RELAXED, __HIP_MEMORY_SCOPE_AGENT); }
; #define XB_SPIN(cond, bar) do { unsigned _sp = 0; while (cond) { __builtin_amdgcn_s_sleep(1); \
;     if ((++_sp & 255u) == 0u) { if (xb_ld(&(bar)[XB_TMO])) break; if (_sp > XB_SPIN_CAP) { atomicAdd(&(bar)[XB_TMO], 1u); break; } } } } while (0)
; __device__ __forceinline__ bool xb_thread0(int wave) { return wave == 0 && hw_lane() == 0; }
;     __device__ __forceinline__ int tid_() const { return wave * 64 + lane_(); }
;     __device__ __forceinline__ void operator()() const {
;         if (sync) { if (xb_thread0(wave)) { XB_SPIN(xb_ld(cnt) < 4u, barw); __builtin_amdgcn_fence(__ATOMIC_ACQUIRE, "agent"); asm volatile("s_waitcnt vmcnt(0)" ::: "memory"); }
;             __syncthreads(); }
;         { const int tid_ = wave * 64 + hw_lane(), r = tid_ & 255, half = tid_ >> 8; const float* sp = ssq + (size_t)(half * 16) * M + r; float s = 0.f;
; #pragma unroll
;           for (int h = 0; h < 16; ++h) s += sp[(size_t)h * M];
.LBB0_847:
	s_cmp_lt_i32 s53, 6
	s_cbranch_scc1 .Llate_pf_done
	s_cmp_eq_u32 s53, 6
	s_cbranch_scc0 .Llate_pf_b
	s_cmp_lg_u32 s60, 0
	s_cbranch_scc1 .Llate_pf_done
	v_mov_b32_e32 v219, 4
	s_andn2_b64 vcc, exec, s[0:1]
	s_cbranch_vccnz .Llate_pf_done
	s_lshl_b32 s99, s14, 8
	s_add_u32 s100, s96, s99
	s_addc_u32 s101, s97, 0
	s_add_u32 s100, s100, 0x12000
	s_addc_u32 s101, s101, 0
	v_mov_b32_e32 v218, 0
	global_load_dword v219, v218, s[100:101] sc1
	s_branch .Llate_pf_done
.Llate_pf_b:
	s_cmp_eq_u32 s53, 8
	s_cbranch_scc0 .Llate_pf_c
	s_cmp_lg_u32 s60, 0
	s_cbranch_scc1 .Llate_pf_done
	v_mov_b32_e32 v218, 0x22000
	ds_write_b32 v218, v219
	buffer_inv sc1
	s_branch .Llate_pf_done
.Llate_pf_c:
	v_mov_b32_e32 v218, 0x22000
	ds_read_b32 v219, v218
	s_waitcnt lgkmcnt(0)
	v_readfirstlane_b32 s99, v219
	s_cmp_lt_u32 s99, 4
	s_cbranch_scc1 .Llate_pf_done
	s_mov_b32 s98, 1
	v_mbcnt_lo_u32_b32 v218, -1, 0
	v_mbcnt_hi_u32_b32 v218, -1, v218
	s_lshl_b32 s99, s14, 10
	v_add_u32_e32 v218, s60, v218
	s_add_u32 s100, s96, s99
	v_lshrrev_b32_e32 v219, 8, v218
	s_addc_u32 s101, s97, 0
	v_and_b32_e32 v218, 0xff, v218
	s_add_u32 s100, s100, 0xfe00000
	v_lshlrev_b32_e32 v218, 2, v218
	s_addc_u32 s101, s101, 0
	v_lshl_or_b32 v218, v219, 20, v218
	global_load_dword v224, v218, s[100:101] sc1
	v_add_u32_e32 v218, 0x10000, v218
	global_load_dword v225, v218, s[100:101] sc1
	v_add_u32_e32 v218, 0x10000, v218
	global_load_dword v226, v218, s[100:101] sc1
	v_add_u32_e32 v218, 0x10000, v218
	global_load_dword v227, v218, s[100:101] sc1
	v_add_u32_e32 v218, 0x10000, v218
	global_load_dword v228, v218, s[100:101] sc1
	v_add_u32_e32 v218, 0x10000, v218
	global_load_dword v229, v218, s[100:101] sc1
	v_add_u32_e32 v218, 0x10000, v218
	global_load_dword v230, v218, s[100:101] sc1
	v_add_u32_e32 v218, 0x10000, v218
	global_load_dword v231, v218, s[100:101] sc1
	v_add_u32_e32 v218, 0x10000, v218
	global_load_dword v232, v218, s[100:101] sc1
	v_add_u32_e32 v218, 0x10000, v218
	global_load_dword v233, v218, s[100:101] sc1
	v_add_u32_e32 v218, 0x10000, v218
	global_load_dword v234, v218, s[100:101] sc1
	v_add_u32_e32 v218, 0x10000, v218
	global_load_dword v235, v218, s[100:101] sc1
	v_add_u32_e32 v218, 0x10000, v218
	global_load_dword v236, v218, s[100:101] sc1
	v_add_u32_e32 v218, 0x10000, v218
	global_load_dword v237, v218, s[100:101] sc1
	v_add_u32_e32 v218, 0x10000, v218
	global_load_dword v238, v218, s[100:101] sc1
	v_add_u32_e32 v218, 0x10000, v218
	global_load_dword v239, v218, s[100:101] sc1
.Llate_pf_done:
	s_nop 0
	ds_read_b128 v[144:147], v141
	ds_read_b128 v[148:151], v141 offset:1024
	ds_read_b128 v[152:155], v141 offset:2048
	ds_read_b128 v[156:159], v141 offset:3072
	ds_read_b128 v[160:163], v140
	ds_read_b128 v[164:167], v140 offset:1024
	ds_read_b128 v[168:171], v140 offset:2048
	ds_read_b128 v[172:175], v140 offset:3072
	s_add_u32 s62, s38, s18
	s_addc_u32 s63, s39, s19
	v_lshl_add_u64 v[208:209], s[62:63], 0, v[130:131]
	s_mov_b32 m0, s51
	v_lshl_add_u64 v[210:211], v[208:209], 0, s[4:5]
	v_mov_b32_e32 v129, v131
	ds_read_b128 v[176:179], v137
	ds_read_b128 v[180:183], v137 offset:1024
	ds_read_b128 v[184:187], v137 offset:2048
	ds_read_b128 v[188:191], v137 offset:3072
	ds_read_b128 v[192:195], v137 offset:4096
	ds_read_b128 v[196:199], v137 offset:5120
	ds_read_b128 v[200:203], v137 offset:6144
	ds_read_b128 v[204:207], v137 offset:7168
	global_load_lds_dwordx4 v[210:211], off
	v_lshl_add_u64 v[210:211], s[62:63], 0, v[128:129]
	v_lshl_add_u64 v[212:213], v[210:211], 0, s[4:5]
	s_mov_b32 m0, s50
	s_nop 0
	global_load_lds_dwordx4 v[212:213], off
	s_cmp_eq_u32 s98, 1
	s_cbranch_scc1 .Llate_w0a
	s_waitcnt vmcnt(8)
	s_branch .Llate_w0b
.Llate_w0a:
	s_waitcnt vmcnt(24)
.Llate_w0b:
	s_waitcnt lgkmcnt(0)
	s_barrier
	s_setprio 1
	s_waitcnt lgkmcnt(0)
	v_mfma_f32_16x16x32_bf16 v[124:127], v[144:147], v[176:179], v[124:127]
	v_mfma_f32_16x16x32_bf16 v[120:123], v[152:155], v[176:179], v[120:123]
	v_mfma_f32_16x16x32_bf16 v[116:119], v[144:147], v[184:187], v[116:119]
	v_mfma_f32_16x16x32_bf16 v[112:115], v[152:155], v[184:187], v[112:115]
	v_mfma_f32_16x16x32_bf16 v[108:111], v[144:147], v[192:195], v[108:111]
	v_mfma_f32_16x16x32_bf16 v[104:107], v[152:155], v[192:195], v[104:107]
	v_mfma_f32_16x16x32_bf16 v[100:103], v[144:147], v[200:203], v[100:103]
	v_mfma_f32_16x16x32_bf16 v[96:99], v[152:155], v[200:203], v[96:99]
	v_mfma_f32_16x16x32_bf16 v[124:127], v[148:151], v[180:183], v[124:127]
	v_mfma_f32_16x16x32_bf16 v[120:123], v[156:159], v[180:183], v[120:123]
	v_mfma_f32_16x16x32_bf16 v[116:119], v[148:151], v[188:191], v[116:119]
	v_mfma_f32_16x16x32_bf16 v[112:115], v[156:159], v[188:191], v[112:115]
	v_mfma_f32_16x16x32_bf16 v[108:111], v[148:151], v[196:199], v[108:111]
	v_mfma_f32_16x16x32_bf16 v[104:107], v[156:159], v[196:199], v[104:107]
	v_mfma_f32_16x16x32_bf16 v[100:103], v[148:151], v[204:207], v[100:103]
	v_mfma_f32_16x16x32_bf16 v[96:99], v[156:159], v[204:207], v[96:99]
	s_setprio 0
	s_setprio 1
	v_mfma_f32_16x16x32_bf16 v[92:95], v[160:163], v[176:179], v[92:95]
	v_mfma_f32_16x16x32_bf16 v[88:91], v[168:171], v[176:179], v[88:91]
	v_mfma_f32_16x16x32_bf16 v[84:87], v[160:163], v[184:187], v[84:87]
	v_mfma_f32_16x16x32_bf16 v[80:83], v[168:171], v[184:187], v[80:83]
	v_mfma_f32_16x16x32_bf16 v[76:79], v[160:163], v[192:195], v[76:79]
	v_mfma_f32_16x16x32_bf16 v[72:75], v[168:171], v[192:195], v[72:75]
	v_mfma_f32_16x16x32_bf16 v[68:71], v[160:163], v[200:203], v[68:71]
	v_mfma_f32_16x16x32_bf16 v[64:67], v[168:171], v[200:203], v[64:67]
	v_mfma_f32_16x16x32_bf16 v[92:95], v[164:167], v[180:183], v[92:95]
	v_mfma_f32_16x16x32_bf16 v[88:91], v[172:175], v[180:183], v[88:91]
	v_mfma_f32_16x16x32_bf16 v[84:87], v[164:167], v[188:191], v[84:87]
	v_mfma_f32_16x16x32_bf16 v[80:83], v[172:175], v[188:191], v[80:83]
	v_mfma_f32_16x16x32_bf16 v[76:79], v[164:167], v[196:199], v[76:79]
	v_mfma_f32_16x16x32_bf16 v[72:75], v[172:175], v[196:199], v[72:75]
	v_mfma_f32_16x16x32_bf16 v[68:71], v[164:167], v[204:207], v[68:71]
	v_mfma_f32_16x16x32_bf16 v[64:67], v[172:175], v[204:207], v[64:67]
	s_setprio 0
	s_barrier
	s_add_u32 s62, s38, s20
	v_mov_b32_e32 v133, v131
	s_addc_u32 s63, s39, s21
	v_lshl_add_u64 v[212:213], s[62:63], 0, v[132:133]
	s_mov_b32 m0, s49
	v_lshl_add_u64 v[214:215], v[212:213], 0, s[6:7]
	v_mov_b32_e32 v135, v131
	ds_read_b128 v[176:179], v137 offset:16384
	ds_read_b128 v[180:183], v137 offset:17408
	ds_read_b128 v[184:187], v137 offset:18432
	ds_read_b128 v[188:191], v137 offset:19456
	ds_read_b128 v[192:195], v137 offset:20480
	ds_read_b128 v[196:199], v137 offset:21504
	ds_read_b128 v[200:203], v137 offset:22528
	ds_read_b128 v[204:207], v137 offset:23552
	global_load_lds_dwordx4 v[214:215], off
	v_lshl_add_u64 v[214:215], s[62:63], 0, v[134:135]
	v_lshl_add_u64 v[216:217], v[214:215], 0, s[6:7]
	s_mov_b32 m0, s47
	s_nop 0
	global_load_lds_dwordx4 v[216:217], off
	v_lshl_add_u64 v[216:217], v[212:213], 0, s[10:11]
	s_mov_b32 m0, s48
	s_nop 0
	global_load_lds_dwordx4 v[216:217], off
	v_lshl_add_u64 v[216:217], v[214:215], 0, s[10:11]
	s_mov_b32 m0, s46
	s_nop 0
	global_load_lds_dwordx4 v[216:217], off
	v_lshl_add_u64 v[216:217], v[208:209], 0, s[24:25]
	s_mov_b32 m0, s40
	s_nop 0
	global_load_lds_dwordx4 v[216:217], off
	v_lshl_add_u64 v[216:217], v[210:211], 0, s[24:25]
	s_mov_b32 m0, s45
	s_nop 0
	global_load_lds_dwordx4 v[216:217], off
	s_cmp_eq_u32 s98, 1
	s_cbranch_scc1 .Llate_w1a
	s_waitcnt vmcnt(8)
	s_branch .Llate_w1b

.Llate_w1b:
	s_waitcnt lgkmcnt(0)
	s_barrier
	s_setprio 1
	s_waitcnt lgkmcnt(0)
	v_mfma_f32_16x16x32_bf16 v[60:63], v[144:147], v[176:179], v[60:63]
	v_mfma_f32_16x16x32_bf16 v[56:59], v[152:155], v[176:179], v[56:59]
	v_mfma_f32_16x16x32_bf16 v[52:55], v[144:147], v[184:187], v[52:55]
	v_mfma_f32_16x16x32_bf16 v[48:51], v[152:155], v[184:187], v[48:51]
	v_mfma_f32_16x16x32_bf16 v[44:47], v[144:147], v[192:195], v[44:47]
	v_mfma_f32_16x16x32_bf16 v[40:43], v[152:155], v[192:195], v[40:43]
	v_mfma_f32_16x16x32_bf16 v[36:39], v[144:147], v[200:203], v[36:39]
	v_mfma_f32_16x16x32_bf16 v[32:35], v[152:155], v[200:203], v[32:35]
	v_mfma_f32_16x16x32_bf16 v[60:63], v[148:151], v[180:183], v[60:63]
	v_mfma_f32_16x16x32_bf16 v[56:59], v[156:159], v[180:183], v[56:59]
	v_mfma_f32_16x16x32_bf16 v[52:55], v[148:151], v[188:191], v[52:55]
	v_mfma_f32_16x16x32_bf16 v[48:51], v[156:159], v[188:191], v[48:51]
	v_mfma_f32_16x16x32_bf16 v[44:47], v[148:151], v[196:199], v[44:47]
	v_mfma_f32_16x16x32_bf16 v[40:43], v[156:159], v[196:199], v[40:43]
	v_mfma_f32_16x16x32_bf16 v[36:39], v[148:151], v[204:207], v[36:39]
	v_mfma_f32_16x16x32_bf16 v[32:35], v[156:159], v[204:207], v[32:35]
	s_setprio 0
	s_setprio 1
	v_mfma_f32_16x16x32_bf16 v[28:31], v[160:163], v[176:179], v[28:31]
	v_mfma_f32_16x16x32_bf16 v[24:27], v[168:171], v[176:179], v[24:27]
	v_mfma_f32_16x16x32_bf16 v[20:23], v[160:163], v[184:187], v[20:23]
	v_mfma_f32_16x16x32_bf16 v[16:19], v[168:171], v[184:187], v[16:19]
	v_mfma_f32_16x16x32_bf16 v[12:15], v[160:163], v[192:195], v[12:15]
	v_mfma_f32_16x16x32_bf16 v[8:11], v[168:171], v[192:195], v[8:11]
	v_mfma_f32_16x16x32_bf16 v[4:7], v[160:163], v[200:203], v[4:7]
	v_mfma_f32_16x16x32_bf16 v[0:3], v[168:171], v[200:203], v[0:3]
	v_mfma_f32_16x16x32_bf16 v[28:31], v[164:167], v[180:183], v[28:31]
	v_mfma_f32_16x16x32_bf16 v[24:27], v[172:175], v[180:183], v[24:27]
	v_mfma_f32_16x16x32_bf16 v[20:23], v[164:167], v[188:191], v[20:23]
	v_mfma_f32_16x16x32_bf16 v[16:19], v[172:175], v[188:191], v[16:19]
	v_mfma_f32_16x16x32_bf16 v[12:15], v[164:167], v[196:199], v[12:15]
	v_mfma_f32_16x16x32_bf16 v[8:11], v[172:175], v[196:199], v[8:11]
	v_mfma_f32_16x16x32_bf16 v[4:7], v[164:167], v[204:207], v[4:7]
	v_mfma_f32_16x16x32_bf16 v[0:3], v[172:175], v[204:207], v[0:3]
	s_setprio 0
	s_barrier
	ds_read_b128 v[144:147], v139
	ds_read_b128 v[148:151], v139 offset:1024
	ds_read_b128 v[152:155], v139 offset:2048
	ds_read_b128 v[156:159], v139 offset:3072
	ds_read_b128 v[160:163], v138
	ds_read_b128 v[164:167], v138 offset:1024
	ds_read_b128 v[168:171], v138 offset:2048
	ds_read_b128 v[172:175], v138 offset:3072
	s_mov_b32 m0, s34
	v_lshl_add_u64 v[216:217], v[208:209], 0, s[26:27]
	ds_read_b128 v[176:179], v137 offset:32768
	ds_read_b128 v[180:183], v137 offset:33792
	ds_read_b128 v[184:187], v137 offset:34816
	ds_read_b128 v[188:191], v137 offset:35840
	ds_read_b128 v[192:195], v137 offset:36864
	ds_read_b128 v[196:199], v137 offset:37888
	ds_read_b128 v[200:203], v137 offset:38912
	ds_read_b128 v[204:207], v137 offset:39936
	global_load_lds_dwordx4 v[216:217], off
	v_lshl_add_u64 v[216:217], v[210:211], 0, s[26:27]
	s_mov_b32 m0, s35
	s_nop 0
	global_load_lds_dwordx4 v[216:217], off
	s_waitcnt vmcnt(8)
	s_waitcnt lgkmcnt(0)
	s_barrier
	s_setprio 1
	s_waitcnt lgkmcnt(0)
	v_mfma_f32_16x16x32_bf16 v[124:127], v[144:147], v[176:179], v[124:127]
	v_mfma_f32_16x16x32_bf16 v[120:123], v[152:155], v[176:179], v[120:123]
	v_mfma_f32_16x16x32_bf16 v[116:119], v[144:147], v[184:187], v[116:119]
	v_mfma_f32_16x16x32_bf16 v[112:115], v[152:155], v[184:187], v[112:115]
	v_mfma_f32_16x16x32_bf16 v[108:111], v[144:147], v[192:195], v[108:111]
	v_mfma_f32_16x16x32_bf16 v[104:107], v[152:155], v[192:195], v[104:107]
	v_mfma_f32_16x16x32_bf16 v[100:103], v[144:147], v[200:203], v[100:103]
	v_mfma_f32_16x16x32_bf16 v[96:99], v[152:155], v[200:203], v[96:99]
	v_mfma_f32_16x16x32_bf16 v[124:127], v[148:151], v[180:183], v[124:127]
	v_mfma_f32_16x16x32_bf16 v[120:123], v[156:159], v[180:183], v[120:123]
	v_mfma_f32_16x16x32_bf16 v[116:119], v[148:151], v[188:191], v[116:119]
	v_mfma_f32_16x16x32_bf16 v[112:115], v[156:159], v[188:191], v[112:115]
	v_mfma_f32_16x16x32_bf16 v[108:111], v[148:151], v[196:199], v[108:111]
	v_mfma_f32_16x16x32_bf16 v[104:107], v[156:159], v[196:199], v[104:107]
	v_mfma_f32_16x16x32_bf16 v[100:103], v[148:151], v[204:207], v[100:103]
	v_mfma_f32_16x16x32_bf16 v[96:99], v[156:159], v[204:207], v[96:99]
	s_setprio 0
	s_setprio 1
	v_mfma_f32_16x16x32_bf16 v[92:95], v[160:163], v[176:179], v[92:95]
	v_mfma_f32_16x16x32_bf16 v[88:91], v[168:171], v[176:179], v[88:91]
	v_mfma_f32_16x16x32_bf16 v[84:87], v[160:163], v[184:187], v[84:87]
	v_mfma_f32_16x16x32_bf16 v[80:83], v[168:171], v[184:187], v[80:83]
	v_mfma_f32_16x16x32_bf16 v[76:79], v[160:163], v[192:195], v[76:79]
	v_mfma_f32_16x16x32_bf16 v[72:75], v[168:171], v[192:195], v[72:75]
	v_mfma_f32_16x16x32_bf16 v[68:71], v[160:163], v[200:203], v[68:71]
	v_mfma_f32_16x16x32_bf16 v[64:67], v[168:171], v[200:203], v[64:67]
	v_mfma_f32_16x16x32_bf16 v[92:95], v[164:167], v[180:183], v[92:95]
	v_mfma_f32_16x16x32_bf16 v[88:91], v[172:175], v[180:183], v[88:91]
	v_mfma_f32_16x16x32_bf16 v[84:87], v[164:167], v[188:191], v[84:87]
	v_mfma_f32_16x16x32_bf16 v[80:83], v[172:175], v[188:191], v[80:83]
	v_mfma_f32_16x16x32_bf16 v[76:79], v[164:167], v[196:199], v[76:79]
	v_mfma_f32_16x16x32_bf16 v[72:75], v[172:175], v[196:199], v[72:75]
	v_mfma_f32_16x16x32_bf16 v[68:71], v[164:167], v[204:207], v[68:71]
	v_mfma_f32_16x16x32_bf16 v[64:67], v[172:175], v[204:207], v[64:67]
	s_setprio 0
	s_barrier
; __device__ __forceinline__ int hw_lane() { int l; asm volatile("v_mbcnt_lo_u32_b32 %0, -1, 0\n\tv_mbcnt_hi_u32_b32 %0, -1, %0" : "=v"(l)); return l; }
; #define PG8_BAR __builtin_amdgcn_s_barrier()
; __device__ __forceinline__ unsigned xb_ld(unsigned* p)              { return __hip_atomic_load(p, __ATOMIC_RELAXED, __HIP_MEMORY_SCOPE_AGENT); }
; #define XB_SPIN(cond, bar) do { unsigned _sp = 0; while (cond) { __builtin_amdgcn_s_sleep(1); \
;     if ((++_sp & 255u) == 0u) { if (xb_ld(&(bar)[XB_TMO])) break; if (_sp > XB_SPIN_CAP) { atomicAdd(&(bar)[XB_TMO], 1u); break; } } } } while (0)
; __device__ __forceinline__ bool xb_thread0(int wave) { return wave == 0 && hw_lane() == 0; }
;     __device__ __forceinline__ int tid_() const { return wave * 64 + lane_(); }
; template <int ROT, class Epi0, class Epi1, class Late, class Post0>
; __device__ __forceinline__ void gemm_phase_pair(PG8_LAS unsigned char* lds, const Gemm g0, const Gemm g1, const Unit u, const Epi0& E0, const Epi1& E1, int wid_in, const Late& late, const Post0& post0) {
;     ...
;     const int t_late = ROT != 0 ? nt0 - ROT - 2 : 0;
;     for (int t = 0; t < t_late; t += 2) {
;         const char* a1 = cA + PG8_KT(t + 1); const char* a2 = cA + PG8_KT(t + 2); const char* b2 = cB + PG8_KT(t + 2); const char* a3 = cA + PG8_KT(t + 3); const char* b3 = cB + PG8_KT(t + 3);
;         PG8_PAIR_ITER(a1 + hs0, vA0, a2, b2, a3, b3, vA0, vB0, hs0);
;     }
;     if (ROT != 0) {
;         if (wr == 0) PG8_BAR;
;         late();
;         if (wr == 1) PG8_BAR;
;     __device__ __forceinline__ void operator()() const {
;         if (sync) { if (xb_thread0(wave)) { XB_SPIN(xb_ld(cnt) < 4u, barw); __builtin_amdgcn_fence(__ATOMIC_ACQUIRE, "agent"); asm volatile("s_waitcnt vmcnt(0)" ::: "memory"); }
;             __syncthreads(); }
;         { const int tid_ = wave * 64 + hw_lane(), r = tid_ & 255, half = tid_ >> 8; const float* sp = ssq + (size_t)(half * 16) * M + r; float s = 0.f;
; #pragma unroll
;           for (int h = 0; h < 16; ++h) s += sp[(size_t)h * M];
;           tab[512 + half * 256 + r] = 1.0f / sqrtf(s * (1.f / 1024.f) + EPS); }
	s_mov_b32 m0, s44
	v_lshl_add_u64 v[216:217], v[212:213], 0, s[28:29]
	ds_read_b128 v[176:179], v137 offset:49152
	ds_read_b128 v[180:183], v137 offset:50176
	ds_read_b128 v[184:187], v137 offset:51200
	ds_read_b128 v[188:191], v137 offset:52224
	ds_read_b128 v[192:195], v137 offset:53248
	ds_read_b128 v[196:199], v137 offset:54272
	ds_read_b128 v[200:203], v137 offset:55296
	ds_read_b128 v[204:207], v137 offset:56320
	global_load_lds_dwordx4 v[216:217], off
	v_lshl_add_u64 v[216:217], v[214:215], 0, s[28:29]
	s_mov_b32 m0, s42
	v_lshl_add_u64 v[212:213], v[212:213], 0, s[30:31]
	global_load_lds_dwordx4 v[216:217], off
	s_mov_b32 m0, s43
	v_lshl_add_u64 v[208:209], v[208:209], 0, s[36:37]
	global_load_lds_dwordx4 v[212:213], off
	v_lshl_add_u64 v[212:213], v[214:215], 0, s[30:31]
	s_mov_b32 m0, s41
	s_nop 0
	global_load_lds_dwordx4 v[212:213], off
	s_mov_b32 m0, s13
	s_nop 0
	global_load_lds_dwordx4 v[208:209], off
	v_lshl_add_u64 v[208:209], v[210:211], 0, s[36:37]
	s_mov_b32 m0, s33
	s_nop 0
	global_load_lds_dwordx4 v[208:209], off
	s_waitcnt vmcnt(8)
	s_waitcnt lgkmcnt(0)
	s_barrier
	s_setprio 1
	s_waitcnt lgkmcnt(0)
	v_mfma_f32_16x16x32_bf16 v[60:63], v[144:147], v[176:179], v[60:63]
	v_mfma_f32_16x16x32_bf16 v[56:59], v[152:155], v[176:179], v[56:59]
	v_mfma_f32_16x16x32_bf16 v[52:55], v[144:147], v[184:187], v[52:55]
	v_mfma_f32_16x16x32_bf16 v[48:51], v[152:155], v[184:187], v[48:51]
	v_mfma_f32_16x16x32_bf16 v[44:47], v[144:147], v[192:195], v[44:47]
	v_mfma_f32_16x16x32_bf16 v[40:43], v[152:155], v[192:195], v[40:43]
	v_mfma_f32_16x16x32_bf16 v[36:39], v[144:147], v[200:203], v[36:39]
	v_mfma_f32_16x16x32_bf16 v[32:35], v[152:155], v[200:203], v[32:35]
	v_mfma_f32_16x16x32_bf16 v[60:63], v[148:151], v[180:183], v[60:63]
	v_mfma_f32_16x16x32_bf16 v[56:59], v[156:159], v[180:183], v[56:59]
	v_mfma_f32_16x16x32_bf16 v[52:55], v[148:151], v[188:191], v[52:55]
	v_mfma_f32_16x16x32_bf16 v[48:51], v[156:159], v[188:191], v[48:51]
	v_mfma_f32_16x16x32_bf16 v[44:47], v[148:151], v[196:199], v[44:47]
	v_mfma_f32_16x16x32_bf16 v[40:43], v[156:159], v[196:199], v[40:43]
	v_mfma_f32_16x16x32_bf16 v[36:39], v[148:151], v[204:207], v[36:39]
	v_mfma_f32_16x16x32_bf16 v[32:35], v[156:159], v[204:207], v[32:35]
	s_setprio 0
	s_setprio 1
	v_mfma_f32_16x16x32_bf16 v[28:31], v[160:163], v[176:179], v[28:31]
	v_mfma_f32_16x16x32_bf16 v[24:27], v[168:171], v[176:179], v[24:27]
	v_mfma_f32_16x16x32_bf16 v[20:23], v[160:163], v[184:187], v[20:23]
	v_mfma_f32_16x16x32_bf16 v[16:19], v[168:171], v[184:187], v[16:19]
	v_mfma_f32_16x16x32_bf16 v[12:15], v[160:163], v[192:195], v[12:15]
	v_mfma_f32_16x16x32_bf16 v[8:11], v[168:171], v[192:195], v[8:11]
	v_mfma_f32_16x16x32_bf16 v[4:7], v[160:163], v[200:203], v[4:7]
	v_mfma_f32_16x16x32_bf16 v[0:3], v[168:171], v[200:203], v[0:3]
	v_mfma_f32_16x16x32_bf16 v[28:31], v[164:167], v[180:183], v[28:31]
	v_mfma_f32_16x16x32_bf16 v[24:27], v[172:175], v[180:183], v[24:27]
	v_mfma_f32_16x16x32_bf16 v[20:23], v[164:167], v[188:191], v[20:23]
	v_mfma_f32_16x16x32_bf16 v[16:19], v[172:175], v[188:191], v[16:19]
	v_mfma_f32_16x16x32_bf16 v[12:15], v[164:167], v[196:199], v[12:15]
	v_mfma_f32_16x16x32_bf16 v[8:11], v[172:175], v[196:199], v[8:11]
	v_mfma_f32_16x16x32_bf16 v[4:7], v[164:167], v[204:207], v[4:7]
	v_mfma_f32_16x16x32_bf16 v[0:3], v[172:175], v[204:207], v[0:3]
	s_setprio 0
	s_barrier
	s_add_i32 s53, s53, 2
	s_add_u32 s38, s38, 0x100
	s_addc_u32 s39, s39, 0
	s_cmp_gt_u32 s53, 11
	s_cbranch_scc0 .LBB0_847
	s_cmpk_lt_u32 s71, 0x100
	s_cselect_b64 s[4:5], -1, 0
	s_and_b64 vcc, exec, s[4:5]
	s_cbranch_vccz .LBB0_850
	s_barrier
.LBB0_850:
	s_lshl_b32 s6, s14, 6
	s_ashr_i32 s7, s6, 31
	s_lshl_b64 s[6:7], s[6:7], 2
	s_add_u32 s6, s96, s6
	s_addc_u32 s7, s97, s7
	s_add_u32 s10, s6, 0x12000
	s_addc_u32 s11, s7, 0
	s_cmp_eq_u32 s98, 1
	s_cbranch_scc0 .Llate_slow
	v_mbcnt_lo_u32_b32 v129, -1, 0
	v_mbcnt_hi_u32_b32 v129, -1, v129
	s_lshl_b32 s6, s14, 8
	v_add_u32_e32 v129, s60, v129
	s_add_i32 s7, 0, 0x20000
	v_and_b32_e32 v146, 0xff, v129
	v_and_b32_e32 v129, 0x3fffff00, v129
	v_lshlrev_b32_e32 v146, 2, v146
	v_lshlrev_b32_e32 v129, 2, v129
	s_mov_b32 s0, 0xf800000
	v_add3_u32 v129, s7, v129, v146
	s_waitcnt vmcnt(8)
	v_add_f32_e32 v131, 0, v224
	v_add_f32_e32 v131, v131, v225
	v_add_f32_e32 v131, v131, v226
	v_add_f32_e32 v131, v131, v227
	v_add_f32_e32 v131, v131, v228
	v_add_f32_e32 v131, v131, v229
	v_add_f32_e32 v131, v131, v230
	v_add_f32_e32 v131, v131, v231
	v_add_f32_e32 v131, v131, v232
	v_add_f32_e32 v131, v131, v233
	v_add_f32_e32 v131, v131, v234
	v_add_f32_e32 v131, v131, v235
	v_add_f32_e32 v131, v131, v236
	v_add_f32_e32 v131, v131, v237
	v_add_f32_e32 v131, v131, v238
	v_add_f32_e32 v131, v131, v239
	v_mov_b32_e32 v133, 0x358637bd
	s_branch .Llate_join
.Llate_slow:
	s_andn2_b64 vcc, exec, s[0:1]
	s_cbranch_vccnz .LBB0_869
	v_readlane_b32 s0, v252, 11
	v_readlane_b32 s1, v252, 12
	s_andn2_b64 vcc, exec, s[0:1]
	s_cbranch_vccnz .LBB0_868
	v_mbcnt_lo_u32_b32 v129, -1, 0
	v_mbcnt_hi_u32_b32 v129, -1, v129
	s_nop 0
	v_cmp_eq_u32_e32 vcc, 0, v129
	s_and_saveexec_b64 s[0:1], vcc
	s_cbranch_execz .LBB0_867
	v_mov_b32_e32 v129, 0
	global_load_dword v131, v129, s[10:11] sc1
	s_waitcnt vmcnt(0)
	v_cmp_lt_u32_e32 vcc, 3, v131
	s_cbranch_vccnz .LBB0_866
	s_mov_b32 s28, 1
	s_branch .LBB0_856

; __device__ __forceinline__ int hw_lane() { int l; asm volatile("v_mbcnt_lo_u32_b32 %0, -1, 0\n\tv_mbcnt_hi_u32_b32 %0, -1, %0" : "=v"(l)); return l; }
;     __device__ __forceinline__ int tid_() const { return wave * 64 + lane_(); }
;     __device__ __forceinline__ void operator()() const {
;     ...
;         { const int tid_ = wave * 64 + hw_lane(), r = tid_ & 255, half = tid_ >> 8; const float* sp = ssq + (size_t)(half * 16) * M + r; float s = 0.f;
; #pragma unroll
;           for (int h = 0; h < 16; ++h) s += sp[(size_t)h * M];
;           tab[512 + half * 256 + r] = 1.0f / sqrtf(s * (1.f / 1024.f) + EPS); }
;         __syncthreads();
;         { const int tid_ = wave * 64 + hw_lane(); if (tid_ < 256) { const float a = tab[512 + tid_], b = tab[768 + tid_]; tab[tid_] = b / a; tab[256 + tid_] = a; } }
;         __syncthreads();
.Llate_join:
	v_fmac_f32_e32 v133, 0x3a800000, v131
	v_mul_f32_e32 v131, 0x4f800000, v133
	v_cmp_gt_f32_e32 vcc, s0, v133
	s_nop 1
	v_cndmask_b32_e32 v131, v133, v131, vcc
	v_sqrt_f32_e32 v133, v131
	s_nop 0
	v_add_u32_e32 v135, -1, v133
	v_fma_f32 v144, -v135, v133, v131
	v_cmp_ge_f32_e64 s[0:1], 0, v144
	v_add_u32_e32 v144, 1, v133
	s_nop 0
	v_cndmask_b32_e64 v135, v133, v135, s[0:1]
	v_fma_f32 v133, -v144, v133, v131
	v_cmp_lt_f32_e64 s[0:1], 0, v133
	s_nop 1
	v_cndmask_b32_e64 v133, v135, v144, s[0:1]
	v_mul_f32_e32 v135, 0x37800000, v133
	v_cndmask_b32_e32 v133, v133, v135, vcc
	v_mov_b32_e32 v135, 0x260
	v_cmp_class_f32_e32 vcc, v131, v135
	s_nop 1
	v_cndmask_b32_e32 v131, v133, v131, vcc
	v_div_scale_f32 v133, s[0:1], v131, v131, 1.0
	v_rcp_f32_e32 v135, v133
	s_movk_i32 s0, 0x100
	v_fma_f32 v144, -v133, v135, 1.0
	v_fmac_f32_e32 v135, v144, v135
	v_div_scale_f32 v144, vcc, 1.0, v131, 1.0
	v_mul_f32_e32 v145, v144, v135
	v_fma_f32 v147, -v133, v145, v144
	v_fmac_f32_e32 v145, v147, v135
	v_fma_f32 v133, -v133, v145, v144
	v_div_fmas_f32 v133, v133, v135, v145
	v_div_fixup_f32 v131, v133, v131, 1.0
	ds_write_b32 v129, v131 offset:2048
	s_waitcnt lgkmcnt(0)
	s_barrier
	v_mbcnt_lo_u32_b32 v129, -1, 0
	v_mbcnt_hi_u32_b32 v129, -1, v129
	s_nop 0
	v_add_u32_e32 v129, s60, v129
	v_cmp_gt_i32_e32 vcc, s0, v129
	s_and_saveexec_b64 s[0:1], vcc
	s_cbranch_execz .LBB0_871
	v_lshl_add_u32 v129, v129, 2, 0
	v_add_u32_e32 v129, 0x20000, v129
	ds_read2st64_b32 v[144:145], v129 offset0:8 offset1:12
	s_waitcnt lgkmcnt(0)
	v_div_scale_f32 v131, s[24:25], v144, v144, v145
	v_rcp_f32_e32 v133, v131
	v_div_scale_f32 v135, vcc, v145, v144, v145
	v_fma_f32 v146, -v131, v133, 1.0
	v_fmac_f32_e32 v133, v146, v133
	v_mul_f32_e32 v146, v135, v133
	v_fma_f32 v147, -v131, v146, v135
	v_fmac_f32_e32 v146, v147, v133
	v_fma_f32 v131, -v131, v146, v135
	v_div_fmas_f32 v131, v131, v133, v146
	v_div_fixup_f32 v131, v131, v144, v145
	ds_write2st64_b32 v129, v131, v144 offset1:4
